# S5 pass B: next u tile prefetched one tile ahead of the output stores, counted vmcnt(4)
# speedup vs baseline: 1.0028x; 1.0028x over previous
; #define LAS __attribute__((address_space(3)))
; DI float lo16(unsigned u) { return __uint_as_float(u << 16); }
; DI float hi16(unsigned u) { return __uint_as_float(u & 0xffff0000u); }
; template <bool PASSB>
; DI void s5_pass(const int tid, LAS unsigned char* lds, const P& p, int G, int c0) {
;     ...
;         { const f32x4* bp = (const f32x4*)(bbar + ((size_t)(g * 64 + lane)) * 32);
; #pragma unroll
;           for (int k = 0; k < 4; ++k) { f32x4 v = bp[k]; bre[4 * k] = v[0]; bre[4 * k + 1] = v[1]; bre[4 * k + 2] = v[2]; bre[4 * k + 3] = v[3]; }
; #pragma unroll
;           for (int k = 0; k < 4; ++k) { f32x4 v = bp[4 + k]; bim[4 * k] = v[0]; bim[4 * k + 1] = v[1]; bim[4 * k + 2] = v[2]; bim[4 * k + 3] = v[3]; } }
;         const float are = abar[(g * 64 + lane) * 2], aim = abar[(g * 64 + lane) * 2 + 1];
;         float hre = 0.f, him = 0.f;
;         bf16x8 cf[4]; float dsk = 0.f;
;         if (PASSB) {
; #pragma unroll
;             for (int ks = 0; ks < 4; ++ks) cf[ks] = *(const bf16x8*)(ccat + ((size_t)(g * 16 + fr)) * 128 + ks * 32 + fq * 8);
;             dsk = dskip[g * 16 + fr];
;             float pr = are, pi = aim;
; #pragma unroll
;             for (int s = 0; s < 8; ++s) { const float nr = pr * pr - pi * pi, ni = 2.f * pr * pi; pr = nr; pi = ni; }
;             for (int s = 0; s < seg; ++s) { const float* he = hend + (((size_t)(b * 16 + g) * 8 + s) * 64 + lane) * 2; const float er = he[0], ei = he[1];
;                 const float nr = pr * hre - pi * him + er, ni = pr * him + pi * hre + ei; hre = nr; him = ni; }
;         }
;         const size_t tokbase = (size_t)b * SEQ + seg * 256;
;         for (int tile = 0; tile < 16; ++tile) {
;             if (lane < 32) { const int tk = lane >> 1, hf = lane & 1;
;                 const u32x4 raw = *(const u32x4*)(us5 + (tokbase + tile * 16 + tk) * 256 + g * 16 + hf * 8);
;                 LAS float* d = ubuf + tk * 16 + hf * 8;
;                 *(LAS f32x4*)d = (f32x4){lo16(raw.x), hi16(raw.x), lo16(raw.y), hi16(raw.y)}; *(LAS f32x4*)(d + 4) = (f32x4){lo16(raw.z), hi16(raw.z), lo16(raw.w), hi16(raw.w)}; }
.LBB0_572:
	s_or_b64 exec, exec, s[8:9]
	v_ashrrev_i32_e32 v63, 31, v62
	s_ashr_i32 s1, s0, 31
	v_lshlrev_b64 v[62:63], 11, v[62:63]
	s_lshl_b64 s[0:1], s[0:1], 1
	v_or_b32_e32 v62, v62, v52
	v_lshl_add_u64 v[64:65], v[54:55], 0, s[0:1]
	v_lshl_add_u64 v[66:67], v[56:57], 0, s[0:1]
	v_mov_b32_e32 v112, v49
	v_mov_b32_e32 v113, 0
	v_lshl_add_u64 v[112:113], v[62:63], 0, v[112:113]
	v_lshlrev_b64 v[112:113], 9, v[112:113]
	v_lshl_add_u64 v[112:113], v[64:65], 0, v[112:113]
	global_load_dwordx4 v[108:111], v[112:113], off
	s_waitcnt vmcnt(0)
	v_mov_b32_e32 v68, v3
	s_waitcnt vmcnt(9)
	v_mov_b32_e32 v69, v47
	v_mov_b32_e32 v3, v46
	v_mov_b32_e32 v46, v1
	v_mov_b32_e32 v47, v45
	v_mov_b32_e32 v1, v44
	v_mov_b32_e32 v44, v7
	s_waitcnt vmcnt(8)
	v_mov_b32_e32 v45, v43
	v_mov_b32_e32 v7, v42
	v_mov_b32_e32 v42, v5
	v_mov_b32_e32 v43, v41
	v_mov_b32_e32 v5, v40
	v_mov_b32_e32 v40, v11
	s_waitcnt vmcnt(7)
	v_mov_b32_e32 v41, v35
	v_mov_b32_e32 v70, v9
	v_mov_b32_e32 v71, v33
	v_mov_b32_e32 v9, v32
	v_mov_b32_e32 v72, v15
	s_waitcnt vmcnt(6)
	v_mov_b32_e32 v73, v39
	v_mov_b32_e32 v15, v38
	v_mov_b32_e32 v38, v13
	v_mov_b32_e32 v39, v37
	v_mov_b32_e32 v13, v36
	v_mov_b32_e32 v11, v34
	s_waitcnt vmcnt(5)
	v_pk_mov_b32 v[36:37], v[60:61], v[60:61] op_sel:[1,0]
	s_mov_b32 s8, 0
.LBB0_573:
	s_and_saveexec_b64 s[0:1], s[6:7]
	s_cbranch_execz .LBB0_575
	s_waitcnt vmcnt(4)
	v_lshlrev_b32_e32 v92, 16, v108
	v_and_b32_e32 v93, 0xffff0000, v108
	v_lshlrev_b32_e32 v94, 16, v109
	v_and_b32_e32 v95, 0xffff0000, v109
	v_lshlrev_b32_e32 v32, 16, v110
	v_and_b32_e32 v33, 0xffff0000, v110
	v_lshlrev_b32_e32 v34, 16, v111
	v_and_b32_e32 v35, 0xffff0000, v111
	ds_write_b128 v79, v[92:95]
	ds_write_b128 v79, v[32:35] offset:16
	s_add_i32 s98, s8, 1
	s_min_u32 s98, s98, 15
	v_lshl_or_b32 v112, s98, 4, v49
	v_mov_b32_e32 v113, 0
	v_lshl_add_u64 v[112:113], v[62:63], 0, v[112:113]
	v_lshlrev_b64 v[112:113], 9, v[112:113]
	v_lshl_add_u64 v[112:113], v[64:65], 0, v[112:113]
	global_load_dwordx4 v[108:111], v[112:113], off

; #define LAS __attribute__((address_space(3)))
; template <bool PASSB>
; DI void s5_pass(const int tid, LAS unsigned char* lds, const P& p, int G, int c0) {
;     ...
;             for (int t = 0; t < 16; ++t) {
;                 float bur = 0.f, bui = 0.f;
; #pragma unroll
;                 for (int k = 0; k < 4; ++k) { const f32x4 u = *(const LAS f32x4*)(ubuf + t * 16 + k * 4);
; #pragma unroll
;                     for (int e = 0; e < 4; ++e) { bur += bre[4 * k + e] * u[e]; bui += bim[4 * k + e] * u[e]; } }
;                 const float nr = are * hre - aim * him + bur, ni = are * him + aim * hre + bui; hre = nr; him = ni;
;                 if (PASSB) { hbuf[t * 136 + lane] = f2bf(hre); hbuf[t * 136 + 64 + lane] = f2bf(-him); }
.LBB0_576:
	v_add_u32_e32 v33, s0, v77
	ds_read_b128 v[92:95], v33
	ds_read_b128 v[96:99], v33 offset:16
	ds_read_b128 v[100:103], v33 offset:32
	ds_read_b128 v[104:107], v33 offset:48
	v_add_u32_e32 v91, v77, v32
	s_waitcnt lgkmcnt(0)
	v_pk_fma_f32 v[34:35], v[12:13], v[92:93], 0 op_sel_hi:[1,0,0]
	v_add_u32_e32 v32, 0x880, v32
	v_pk_fma_f32 v[34:35], v[38:39], v[92:93], v[34:35] op_sel:[0,1,0]
	v_mov_b32_e32 v92, v95
	v_pk_fma_f32 v[34:35], v[14:15], v[94:95], v[34:35] op_sel_hi:[1,0,1]
	s_waitcnt lgkmcnt(2)
	v_mov_b32_e32 v94, v99
	v_pk_fma_f32 v[34:35], v[72:73], v[92:93], v[34:35] op_sel_hi:[1,0,1]
	v_pk_mul_f32 v[92:93], v[36:37], v[74:75] op_sel:[0,1]
	v_pk_fma_f32 v[34:35], v[8:9], v[96:97], v[34:35] op_sel_hi:[1,0,1]
	s_nop 0
	v_pk_fma_f32 v[34:35], v[70:71], v[96:97], v[34:35] op_sel:[0,1,0]
	s_nop 0
	v_pk_fma_f32 v[34:35], v[10:11], v[98:99], v[34:35] op_sel_hi:[1,0,1]
	s_nop 0
	v_pk_fma_f32 v[34:35], v[40:41], v[94:95], v[34:35] op_sel_hi:[1,0,1]
	s_waitcnt lgkmcnt(1)
	v_mov_b32_e32 v94, v103
	v_pk_fma_f32 v[34:35], v[4:5], v[100:101], v[34:35] op_sel_hi:[1,0,1]
	s_nop 0
	v_pk_fma_f32 v[34:35], v[42:43], v[100:101], v[34:35] op_sel:[0,1,0]
	s_nop 0
	v_pk_fma_f32 v[34:35], v[6:7], v[102:103], v[34:35] op_sel_hi:[1,0,1]
	s_nop 0
	v_pk_fma_f32 v[34:35], v[44:45], v[94:95], v[34:35] op_sel_hi:[1,0,1]
	s_waitcnt lgkmcnt(0)
	v_mov_b32_e32 v94, v107
	v_pk_fma_f32 v[34:35], v[0:1], v[104:105], v[34:35] op_sel_hi:[1,0,1]
	s_nop 0
	v_pk_fma_f32 v[34:35], v[46:47], v[104:105], v[34:35] op_sel:[0,1,0]
	s_nop 0
	v_pk_fma_f32 v[34:35], v[2:3], v[106:107], v[34:35] op_sel_hi:[1,0,1]
	s_nop 0
	v_pk_fma_f32 v[34:35], v[68:69], v[94:95], v[34:35] op_sel_hi:[1,0,1]
	v_pk_fma_f32 v[94:95], v[60:61], v[74:75], v[92:93] neg_lo:[0,0,1] neg_hi:[0,0,1]
	v_pk_fma_f32 v[74:75], v[60:61], v[74:75], v[92:93] op_sel_hi:[1,0,1]
	s_nop 0
	v_mov_b32_e32 v95, v75
	v_pk_add_f32 v[34:35], v[94:95], v[34:35]
	s_nop 0
	v_cvt_pk_bf16_f32 v74, v34, s0
	ds_write_b16 v91, v74
	v_cvt_pk_bf16_f32 v74, -v35, s0
	ds_write_b16 v91, v74 offset:128
	ds_read_b128 v[92:95], v33 offset:64
	ds_read_b128 v[96:99], v33 offset:80
	ds_read_b128 v[100:103], v33 offset:96
	ds_read_b128 v[104:107], v33 offset:112
	s_waitcnt lgkmcnt(3)
	v_pk_fma_f32 v[74:75], v[12:13], v[92:93], 0 op_sel_hi:[1,0,0]
	s_nop 0
	v_pk_fma_f32 v[74:75], v[38:39], v[92:93], v[74:75] op_sel:[0,1,0]
	v_mov_b32_e32 v92, v95
	v_pk_fma_f32 v[74:75], v[14:15], v[94:95], v[74:75] op_sel_hi:[1,0,1]
	s_waitcnt lgkmcnt(2)
	v_mov_b32_e32 v94, v99
	v_pk_fma_f32 v[74:75], v[72:73], v[92:93], v[74:75] op_sel_hi:[1,0,1]
	v_pk_mul_f32 v[92:93], v[36:37], v[34:35] op_sel:[0,1]
	v_pk_fma_f32 v[74:75], v[8:9], v[96:97], v[74:75] op_sel_hi:[1,0,1]
	s_nop 0
	v_pk_fma_f32 v[74:75], v[70:71], v[96:97], v[74:75] op_sel:[0,1,0]
	s_nop 0
	v_pk_fma_f32 v[74:75], v[10:11], v[98:99], v[74:75] op_sel_hi:[1,0,1]
	s_nop 0
	v_pk_fma_f32 v[74:75], v[40:41], v[94:95], v[74:75] op_sel_hi:[1,0,1]
	s_waitcnt lgkmcnt(1)
	v_mov_b32_e32 v94, v103
	v_pk_fma_f32 v[74:75], v[4:5], v[100:101], v[74:75] op_sel_hi:[1,0,1]
	s_nop 0
	v_pk_fma_f32 v[74:75], v[42:43], v[100:101], v[74:75] op_sel:[0,1,0]
	s_nop 0
	v_pk_fma_f32 v[74:75], v[6:7], v[102:103], v[74:75] op_sel_hi:[1,0,1]
	s_nop 0
	v_pk_fma_f32 v[74:75], v[44:45], v[94:95], v[74:75] op_sel_hi:[1,0,1]
	s_waitcnt lgkmcnt(0)
	v_mov_b32_e32 v94, v107
	v_pk_fma_f32 v[74:75], v[0:1], v[104:105], v[74:75] op_sel_hi:[1,0,1]
	s_nop 0
	v_pk_fma_f32 v[74:75], v[46:47], v[104:105], v[74:75] op_sel:[0,1,0]
	s_nop 0
	v_pk_fma_f32 v[74:75], v[2:3], v[106:107], v[74:75] op_sel_hi:[1,0,1]
	s_nop 0
	v_pk_fma_f32 v[74:75], v[68:69], v[94:95], v[74:75] op_sel_hi:[1,0,1]
	v_pk_fma_f32 v[94:95], v[60:61], v[34:35], v[92:93] neg_lo:[0,0,1] neg_hi:[0,0,1]
	v_pk_fma_f32 v[34:35], v[60:61], v[34:35], v[92:93] op_sel_hi:[1,0,1]
	s_nop 0
	v_mov_b32_e32 v95, v35
	v_pk_add_f32 v[34:35], v[94:95], v[74:75]
	s_nop 0
	v_cvt_pk_bf16_f32 v74, v34, s0
	ds_write_b16 v91, v74 offset:272
	v_cvt_pk_bf16_f32 v74, -v35, s0
	ds_write_b16 v91, v74 offset:400
	ds_read_b128 v[92:95], v33 offset:128
	ds_read_b128 v[96:99], v33 offset:144
	ds_read_b128 v[100:103], v33 offset:160
	ds_read_b128 v[104:107], v33 offset:176
	s_waitcnt lgkmcnt(3)
	v_pk_fma_f32 v[74:75], v[12:13], v[92:93], 0 op_sel_hi:[1,0,0]
	s_nop 0
	v_pk_fma_f32 v[74:75], v[38:39], v[92:93], v[74:75] op_sel:[0,1,0]
	v_mov_b32_e32 v92, v95
	v_pk_fma_f32 v[74:75], v[14:15], v[94:95], v[74:75] op_sel_hi:[1,0,1]
	s_waitcnt lgkmcnt(2)
	v_mov_b32_e32 v94, v99
	v_pk_fma_f32 v[74:75], v[72:73], v[92:93], v[74:75] op_sel_hi:[1,0,1]
	v_pk_mul_f32 v[92:93], v[36:37], v[34:35] op_sel:[0,1]
	v_pk_fma_f32 v[74:75], v[8:9], v[96:97], v[74:75] op_sel_hi:[1,0,1]
	s_nop 0
	v_pk_fma_f32 v[74:75], v[70:71], v[96:97], v[74:75] op_sel:[0,1,0]
	s_nop 0
	v_pk_fma_f32 v[74:75], v[10:11], v[98:99], v[74:75] op_sel_hi:[1,0,1]
	s_nop 0
	v_pk_fma_f32 v[74:75], v[40:41], v[94:95], v[74:75] op_sel_hi:[1,0,1]
	s_waitcnt lgkmcnt(1)
	v_mov_b32_e32 v94, v103
	v_pk_fma_f32 v[74:75], v[4:5], v[100:101], v[74:75] op_sel_hi:[1,0,1]
	s_nop 0
	v_pk_fma_f32 v[74:75], v[42:43], v[100:101], v[74:75] op_sel:[0,1,0]
	s_nop 0
	v_pk_fma_f32 v[74:75], v[6:7], v[102:103], v[74:75] op_sel_hi:[1,0,1]
	s_nop 0
	v_pk_fma_f32 v[74:75], v[44:45], v[94:95], v[74:75] op_sel_hi:[1,0,1]
	s_waitcnt lgkmcnt(0)
; #define LAS __attribute__((address_space(3)))
; template <bool PASSB>
; DI void s5_pass(const int tid, LAS unsigned char* lds, const P& p, int G, int c0) {
;     ...
;             for (int t = 0; t < 16; ++t) {
;                 float bur = 0.f, bui = 0.f;
; #pragma unroll
;                 for (int k = 0; k < 4; ++k) { const f32x4 u = *(const LAS f32x4*)(ubuf + t * 16 + k * 4);
; #pragma unroll
;                     for (int e = 0; e < 4; ++e) { bur += bre[4 * k + e] * u[e]; bui += bim[4 * k + e] * u[e]; } }
;                 const float nr = are * hre - aim * him + bur, ni = are * him + aim * hre + bui; hre = nr; him = ni;
;                 if (PASSB) { hbuf[t * 136 + lane] = f2bf(hre); hbuf[t * 136 + 64 + lane] = f2bf(-him); }
	v_mov_b32_e32 v94, v107
	v_pk_fma_f32 v[74:75], v[0:1], v[104:105], v[74:75] op_sel_hi:[1,0,1]
	s_nop 0
	v_pk_fma_f32 v[74:75], v[46:47], v[104:105], v[74:75] op_sel:[0,1,0]
	s_nop 0
	v_pk_fma_f32 v[74:75], v[2:3], v[106:107], v[74:75] op_sel_hi:[1,0,1]
	s_nop 0
	v_pk_fma_f32 v[74:75], v[68:69], v[94:95], v[74:75] op_sel_hi:[1,0,1]
	v_pk_fma_f32 v[94:95], v[60:61], v[34:35], v[92:93] neg_lo:[0,0,1] neg_hi:[0,0,1]
	v_pk_fma_f32 v[34:35], v[60:61], v[34:35], v[92:93] op_sel_hi:[1,0,1]
	s_nop 0
	v_mov_b32_e32 v95, v35
	v_pk_add_f32 v[34:35], v[94:95], v[74:75]
	s_nop 0
	v_cvt_pk_bf16_f32 v74, v34, s0
	ds_write_b16 v91, v74 offset:544
	v_cvt_pk_bf16_f32 v74, -v35, s0
	ds_write_b16 v91, v74 offset:672
	ds_read_b128 v[92:95], v33 offset:192
	ds_read_b128 v[96:99], v33 offset:208
	ds_read_b128 v[100:103], v33 offset:224
	ds_read_b128 v[104:107], v33 offset:240
	s_waitcnt lgkmcnt(3)
	v_pk_fma_f32 v[74:75], v[12:13], v[92:93], 0 op_sel_hi:[1,0,0]
	s_nop 0
	v_pk_fma_f32 v[74:75], v[38:39], v[92:93], v[74:75] op_sel:[0,1,0]
	v_mov_b32_e32 v92, v95
	v_pk_fma_f32 v[74:75], v[14:15], v[94:95], v[74:75] op_sel_hi:[1,0,1]
	s_waitcnt lgkmcnt(2)
	v_mov_b32_e32 v94, v99
	v_pk_fma_f32 v[74:75], v[72:73], v[92:93], v[74:75] op_sel_hi:[1,0,1]
	v_pk_mul_f32 v[92:93], v[36:37], v[34:35] op_sel:[0,1]
	v_pk_fma_f32 v[74:75], v[8:9], v[96:97], v[74:75] op_sel_hi:[1,0,1]
	s_nop 0
	v_pk_fma_f32 v[74:75], v[70:71], v[96:97], v[74:75] op_sel:[0,1,0]
	s_nop 0
	v_pk_fma_f32 v[74:75], v[10:11], v[98:99], v[74:75] op_sel_hi:[1,0,1]
	s_nop 0
	v_pk_fma_f32 v[74:75], v[40:41], v[94:95], v[74:75] op_sel_hi:[1,0,1]
	s_waitcnt lgkmcnt(1)
	v_mov_b32_e32 v94, v103
	v_pk_fma_f32 v[74:75], v[4:5], v[100:101], v[74:75] op_sel_hi:[1,0,1]
	s_nop 0
	v_pk_fma_f32 v[74:75], v[42:43], v[100:101], v[74:75] op_sel:[0,1,0]
	s_nop 0
	v_pk_fma_f32 v[74:75], v[6:7], v[102:103], v[74:75] op_sel_hi:[1,0,1]
	s_nop 0
	v_pk_fma_f32 v[74:75], v[44:45], v[94:95], v[74:75] op_sel_hi:[1,0,1]
	s_waitcnt lgkmcnt(0)
	v_mov_b32_e32 v94, v107
	v_pk_fma_f32 v[74:75], v[0:1], v[104:105], v[74:75] op_sel_hi:[1,0,1]
	s_nop 0
	v_pk_fma_f32 v[74:75], v[46:47], v[104:105], v[74:75] op_sel:[0,1,0]
	s_nop 0
	v_pk_fma_f32 v[74:75], v[2:3], v[106:107], v[74:75] op_sel_hi:[1,0,1]
	s_nop 0
	v_pk_fma_f32 v[74:75], v[68:69], v[94:95], v[74:75] op_sel_hi:[1,0,1]
	v_pk_fma_f32 v[94:95], v[60:61], v[34:35], v[92:93] neg_lo:[0,0,1] neg_hi:[0,0,1]
	v_pk_fma_f32 v[34:35], v[60:61], v[34:35], v[92:93] op_sel_hi:[1,0,1]
	s_nop 0
	v_mov_b32_e32 v95, v35
	v_pk_add_f32 v[34:35], v[94:95], v[74:75]
	s_nop 0
	v_cvt_pk_bf16_f32 v74, v34, s0
	ds_write_b16 v91, v74 offset:816
	v_cvt_pk_bf16_f32 v74, -v35, s0
	ds_write_b16 v91, v74 offset:944
	ds_read_b128 v[92:95], v33 offset:256
	ds_read_b128 v[96:99], v33 offset:272
	ds_read_b128 v[100:103], v33 offset:288
	ds_read_b128 v[104:107], v33 offset:304
	s_waitcnt lgkmcnt(3)
	v_pk_fma_f32 v[74:75], v[12:13], v[92:93], 0 op_sel_hi:[1,0,0]
	s_nop 0
	v_pk_fma_f32 v[74:75], v[38:39], v[92:93], v[74:75] op_sel:[0,1,0]
	v_mov_b32_e32 v92, v95
	v_pk_fma_f32 v[74:75], v[14:15], v[94:95], v[74:75] op_sel_hi:[1,0,1]
	s_waitcnt lgkmcnt(2)
	v_mov_b32_e32 v94, v99
	v_pk_fma_f32 v[74:75], v[72:73], v[92:93], v[74:75] op_sel_hi:[1,0,1]
	v_pk_mul_f32 v[92:93], v[36:37], v[34:35] op_sel:[0,1]
	v_pk_fma_f32 v[74:75], v[8:9], v[96:97], v[74:75] op_sel_hi:[1,0,1]
	s_nop 0
	v_pk_fma_f32 v[74:75], v[70:71], v[96:97], v[74:75] op_sel:[0,1,0]
	s_nop 0
	v_pk_fma_f32 v[74:75], v[10:11], v[98:99], v[74:75] op_sel_hi:[1,0,1]
	s_nop 0
	v_pk_fma_f32 v[74:75], v[40:41], v[94:95], v[74:75] op_sel_hi:[1,0,1]
	s_waitcnt lgkmcnt(1)
	v_mov_b32_e32 v94, v103
	v_pk_fma_f32 v[74:75], v[4:5], v[100:101], v[74:75] op_sel_hi:[1,0,1]
	s_nop 0
	v_pk_fma_f32 v[74:75], v[42:43], v[100:101], v[74:75] op_sel:[0,1,0]
	s_nop 0
	v_pk_fma_f32 v[74:75], v[6:7], v[102:103], v[74:75] op_sel_hi:[1,0,1]
	s_nop 0
	v_pk_fma_f32 v[74:75], v[44:45], v[94:95], v[74:75] op_sel_hi:[1,0,1]
	s_waitcnt lgkmcnt(0)
	v_mov_b32_e32 v94, v107
	v_pk_fma_f32 v[74:75], v[0:1], v[104:105], v[74:75] op_sel_hi:[1,0,1]
	s_nop 0
	v_pk_fma_f32 v[74:75], v[46:47], v[104:105], v[74:75] op_sel:[0,1,0]
	s_nop 0
	v_pk_fma_f32 v[74:75], v[2:3], v[106:107], v[74:75] op_sel_hi:[1,0,1]
	s_nop 0
	v_pk_fma_f32 v[74:75], v[68:69], v[94:95], v[74:75] op_sel_hi:[1,0,1]
	v_pk_fma_f32 v[94:95], v[60:61], v[34:35], v[92:93] neg_lo:[0,0,1] neg_hi:[0,0,1]
	v_pk_fma_f32 v[34:35], v[60:61], v[34:35], v[92:93] op_sel_hi:[1,0,1]
	s_nop 0
	v_mov_b32_e32 v95, v35
	v_pk_add_f32 v[34:35], v[94:95], v[74:75]
	s_nop 0
	v_cvt_pk_bf16_f32 v74, v34, s0
	ds_write_b16 v91, v74 offset:1088
	v_cvt_pk_bf16_f32 v74, -v35, s0
	ds_write_b16 v91, v74 offset:1216
	ds_read_b128 v[92:95], v33 offset:320
	ds_read_b128 v[96:99], v33 offset:336
	ds_read_b128 v[100:103], v33 offset:352
	ds_read_b128 v[104:107], v33 offset:368
	s_waitcnt lgkmcnt(3)
	v_pk_fma_f32 v[74:75], v[12:13], v[92:93], 0 op_sel_hi:[1,0,0]
	s_nop 0
	v_pk_fma_f32 v[74:75], v[38:39], v[92:93], v[74:75] op_sel:[0,1,0]
	v_mov_b32_e32 v92, v95
	v_pk_fma_f32 v[74:75], v[14:15], v[94:95], v[74:75] op_sel_hi:[1,0,1]
	s_waitcnt lgkmcnt(2)
	v_mov_b32_e32 v94, v99
	v_pk_fma_f32 v[74:75], v[72:73], v[92:93], v[74:75] op_sel_hi:[1,0,1]
	v_pk_mul_f32 v[92:93], v[36:37], v[34:35] op_sel:[0,1]
	v_pk_fma_f32 v[74:75], v[8:9], v[96:97], v[74:75] op_sel_hi:[1,0,1]
	s_nop 0
	v_pk_fma_f32 v[74:75], v[70:71], v[96:97], v[74:75] op_sel:[0,1,0]
	s_nop 0
	v_pk_fma_f32 v[74:75], v[10:11], v[98:99], v[74:75] op_sel_hi:[1,0,1]
	s_nop 0
	v_pk_fma_f32 v[74:75], v[40:41], v[94:95], v[74:75] op_sel_hi:[1,0,1]
	s_waitcnt lgkmcnt(1)
; #define LAS __attribute__((address_space(3)))
; template <bool PASSB>
; DI void s5_pass(const int tid, LAS unsigned char* lds, const P& p, int G, int c0) {
;     ...
;             for (int t = 0; t < 16; ++t) {
;                 float bur = 0.f, bui = 0.f;
; #pragma unroll
;                 for (int k = 0; k < 4; ++k) { const f32x4 u = *(const LAS f32x4*)(ubuf + t * 16 + k * 4);
; #pragma unroll
;                     for (int e = 0; e < 4; ++e) { bur += bre[4 * k + e] * u[e]; bui += bim[4 * k + e] * u[e]; } }
;                 const float nr = are * hre - aim * him + bur, ni = are * him + aim * hre + bui; hre = nr; him = ni;
;                 if (PASSB) { hbuf[t * 136 + lane] = f2bf(hre); hbuf[t * 136 + 64 + lane] = f2bf(-him); }
	v_mov_b32_e32 v94, v103
	v_pk_fma_f32 v[74:75], v[4:5], v[100:101], v[74:75] op_sel_hi:[1,0,1]
	s_nop 0
	v_pk_fma_f32 v[74:75], v[42:43], v[100:101], v[74:75] op_sel:[0,1,0]
	s_nop 0
	v_pk_fma_f32 v[74:75], v[6:7], v[102:103], v[74:75] op_sel_hi:[1,0,1]
	s_nop 0
	v_pk_fma_f32 v[74:75], v[44:45], v[94:95], v[74:75] op_sel_hi:[1,0,1]
	s_waitcnt lgkmcnt(0)
	v_mov_b32_e32 v94, v107
	v_pk_fma_f32 v[74:75], v[0:1], v[104:105], v[74:75] op_sel_hi:[1,0,1]
	s_nop 0
	v_pk_fma_f32 v[74:75], v[46:47], v[104:105], v[74:75] op_sel:[0,1,0]
	s_nop 0
	v_pk_fma_f32 v[74:75], v[2:3], v[106:107], v[74:75] op_sel_hi:[1,0,1]
	s_nop 0
	v_pk_fma_f32 v[74:75], v[68:69], v[94:95], v[74:75] op_sel_hi:[1,0,1]
	v_pk_fma_f32 v[94:95], v[60:61], v[34:35], v[92:93] neg_lo:[0,0,1] neg_hi:[0,0,1]
	v_pk_fma_f32 v[34:35], v[60:61], v[34:35], v[92:93] op_sel_hi:[1,0,1]
	s_nop 0
	v_mov_b32_e32 v95, v35
	v_pk_add_f32 v[34:35], v[94:95], v[74:75]
	s_nop 0
	v_cvt_pk_bf16_f32 v74, v34, s0
	ds_write_b16 v91, v74 offset:1360
	v_cvt_pk_bf16_f32 v74, -v35, s0
	ds_write_b16 v91, v74 offset:1488
	ds_read_b128 v[92:95], v33 offset:384
	ds_read_b128 v[96:99], v33 offset:400
	ds_read_b128 v[100:103], v33 offset:416
	ds_read_b128 v[104:107], v33 offset:432
	s_waitcnt lgkmcnt(3)
	v_pk_fma_f32 v[74:75], v[12:13], v[92:93], 0 op_sel_hi:[1,0,0]
	s_nop 0
	v_pk_fma_f32 v[74:75], v[38:39], v[92:93], v[74:75] op_sel:[0,1,0]
	v_mov_b32_e32 v92, v95
	v_pk_fma_f32 v[74:75], v[14:15], v[94:95], v[74:75] op_sel_hi:[1,0,1]
	s_waitcnt lgkmcnt(2)
	v_mov_b32_e32 v94, v99
	v_pk_fma_f32 v[74:75], v[72:73], v[92:93], v[74:75] op_sel_hi:[1,0,1]
	v_pk_mul_f32 v[92:93], v[36:37], v[34:35] op_sel:[0,1]
	v_pk_fma_f32 v[74:75], v[8:9], v[96:97], v[74:75] op_sel_hi:[1,0,1]
	s_nop 0
	v_pk_fma_f32 v[74:75], v[70:71], v[96:97], v[74:75] op_sel:[0,1,0]
	s_nop 0
	v_pk_fma_f32 v[74:75], v[10:11], v[98:99], v[74:75] op_sel_hi:[1,0,1]
	s_nop 0
	v_pk_fma_f32 v[74:75], v[40:41], v[94:95], v[74:75] op_sel_hi:[1,0,1]
	s_waitcnt lgkmcnt(1)
	v_mov_b32_e32 v94, v103
	v_pk_fma_f32 v[74:75], v[4:5], v[100:101], v[74:75] op_sel_hi:[1,0,1]
	s_nop 0
	v_pk_fma_f32 v[74:75], v[42:43], v[100:101], v[74:75] op_sel:[0,1,0]
	s_nop 0
	v_pk_fma_f32 v[74:75], v[6:7], v[102:103], v[74:75] op_sel_hi:[1,0,1]
	s_nop 0
	v_pk_fma_f32 v[74:75], v[44:45], v[94:95], v[74:75] op_sel_hi:[1,0,1]
	s_waitcnt lgkmcnt(0)
	v_mov_b32_e32 v94, v107
	v_pk_fma_f32 v[74:75], v[0:1], v[104:105], v[74:75] op_sel_hi:[1,0,1]
	s_nop 0
	v_pk_fma_f32 v[74:75], v[46:47], v[104:105], v[74:75] op_sel:[0,1,0]
	s_nop 0
	v_pk_fma_f32 v[74:75], v[2:3], v[106:107], v[74:75] op_sel_hi:[1,0,1]
	s_nop 0
	v_pk_fma_f32 v[74:75], v[68:69], v[94:95], v[74:75] op_sel_hi:[1,0,1]
	v_pk_fma_f32 v[94:95], v[60:61], v[34:35], v[92:93] neg_lo:[0,0,1] neg_hi:[0,0,1]
	v_pk_fma_f32 v[34:35], v[60:61], v[34:35], v[92:93] op_sel_hi:[1,0,1]
	s_nop 0
	v_mov_b32_e32 v95, v35
	v_pk_add_f32 v[34:35], v[94:95], v[74:75]
	s_nop 0
	v_cvt_pk_bf16_f32 v74, v34, s0
	ds_write_b16 v91, v74 offset:1632
	v_cvt_pk_bf16_f32 v74, -v35, s0
	ds_write_b16 v91, v74 offset:1760
	ds_read_b128 v[92:95], v33 offset:448
	ds_read_b128 v[96:99], v33 offset:464
	ds_read_b128 v[100:103], v33 offset:480
	ds_read_b128 v[104:107], v33 offset:496
	s_waitcnt lgkmcnt(3)
	v_pk_fma_f32 v[74:75], v[12:13], v[92:93], 0 op_sel_hi:[1,0,0]
	s_nop 0
	v_pk_fma_f32 v[74:75], v[38:39], v[92:93], v[74:75] op_sel:[0,1,0]
	v_mov_b32_e32 v92, v95
	v_pk_fma_f32 v[74:75], v[14:15], v[94:95], v[74:75] op_sel_hi:[1,0,1]
	s_waitcnt lgkmcnt(2)
	v_mov_b32_e32 v94, v99
	v_pk_fma_f32 v[74:75], v[72:73], v[92:93], v[74:75] op_sel_hi:[1,0,1]
	v_pk_mul_f32 v[92:93], v[36:37], v[34:35] op_sel:[0,1]
	v_pk_fma_f32 v[74:75], v[8:9], v[96:97], v[74:75] op_sel_hi:[1,0,1]
	s_nop 0
	v_pk_fma_f32 v[74:75], v[70:71], v[96:97], v[74:75] op_sel:[0,1,0]
	s_nop 0
	v_pk_fma_f32 v[74:75], v[10:11], v[98:99], v[74:75] op_sel_hi:[1,0,1]
	s_nop 0
	v_pk_fma_f32 v[74:75], v[40:41], v[94:95], v[74:75] op_sel_hi:[1,0,1]
	s_waitcnt lgkmcnt(1)
	v_mov_b32_e32 v94, v103
	v_pk_fma_f32 v[74:75], v[4:5], v[100:101], v[74:75] op_sel_hi:[1,0,1]
	s_nop 0
	v_pk_fma_f32 v[74:75], v[42:43], v[100:101], v[74:75] op_sel:[0,1,0]
	s_nop 0
	v_pk_fma_f32 v[74:75], v[6:7], v[102:103], v[74:75] op_sel_hi:[1,0,1]
	s_nop 0
	v_pk_fma_f32 v[74:75], v[44:45], v[94:95], v[74:75] op_sel_hi:[1,0,1]
	s_waitcnt lgkmcnt(0)
	v_mov_b32_e32 v94, v107
	v_pk_fma_f32 v[74:75], v[0:1], v[104:105], v[74:75] op_sel_hi:[1,0,1]
	s_nop 0
	v_pk_fma_f32 v[74:75], v[46:47], v[104:105], v[74:75] op_sel:[0,1,0]
	s_nop 0
	v_pk_fma_f32 v[74:75], v[2:3], v[106:107], v[74:75] op_sel_hi:[1,0,1]
	s_nop 0
	v_pk_fma_f32 v[74:75], v[68:69], v[94:95], v[74:75] op_sel_hi:[1,0,1]
	v_pk_fma_f32 v[94:95], v[60:61], v[34:35], v[92:93] neg_lo:[0,0,1] neg_hi:[0,0,1]
	v_pk_fma_f32 v[34:35], v[60:61], v[34:35], v[92:93] op_sel_hi:[1,0,1]
	s_nop 0
	v_mov_b32_e32 v95, v35
	v_pk_add_f32 v[74:75], v[94:95], v[74:75]
	s_nop 0
	v_cvt_pk_bf16_f32 v33, v74, s0
	ds_write_b16 v91, v33 offset:1904
	v_cvt_pk_bf16_f32 v33, -v75, s0
	s_addk_i32 s0, 0x200
	s_cmpk_lg_i32 s0, 0x400
	ds_write_b16 v91, v33 offset:2032
	s_cbranch_scc1 .LBB0_576
; #define LAS __attribute__((address_space(3)))
; DI float gelu_tanh(float x) { float u = 0.7978845608028654f * (x + 0.044715f * x * x * x); float e = __expf(2.f * u); float th = 1.f - 2.f / (e + 1.f); return 0.5f * x * (1.f + th); }
; DI f32x4 mfma16(bf16x8 a, bf16x8 b, f32x4 c) { return __builtin_amdgcn_mfma_f32_16x16x32_bf16(a, b, c, 0, 0, 0); }
; DI void lds_wait() { asm volatile("s_waitcnt lgkmcnt(0)" ::: "memory"); }
; template <bool PASSB>
; DI void s5_pass(const int tid, LAS unsigned char* lds, const P& p, int G, int c0) {
;     ...
;             if (PASSB) {
;                 lds_wait();
;                 f32x4 acc = (f32x4){0.f, 0.f, 0.f, 0.f};
; #pragma unroll
;                 for (int ks = 0; ks < 4; ++ks) { const bf16x8 a = *(const LAS bf16x8*)(hbuf + fr * 136 + ks * 32 + fq * 8); acc = mfma16(a, cf[ks], acc); }
; #pragma unroll
;                 for (int j = 0; j < 4; ++j) { const int tk = fq * 4 + j; const float y = acc[j] + dsk * ubuf[tk * 16 + fr];
;                     zs5[(tokbase + tile * 16 + tk) * 256 + g * 16 + fr] = f2bf(gelu_tanh(y)); }
;             }
;             lds_wait();
;         }
	s_waitcnt lgkmcnt(0)
	v_add_u32_e32 v91, v80, v48
	ds_read_b128 v[32:35], v91 offset:1024
	ds_read_b128 v[92:95], v91 offset:1088
	s_lshl_b32 s0, s8, 4
	s_add_i32 s8, s8, 1
	s_cmp_eq_u32 s8, 16
	s_waitcnt lgkmcnt(1)
	v_mfma_f32_16x16x32_bf16 v[32:35], v[32:35], v[16:19], 0
	s_waitcnt lgkmcnt(0)
	v_mfma_f32_16x16x32_bf16 v[32:35], v[92:95], v[20:23], v[32:35]
	ds_read_b128 v[92:95], v91 offset:1152
	s_waitcnt lgkmcnt(0)
	v_mfma_f32_16x16x32_bf16 v[32:35], v[92:95], v[24:27], v[32:35]
	ds_read_b128 v[92:95], v91 offset:1216
	ds_read_b32 v91, v86
	s_waitcnt lgkmcnt(1)
	v_mfma_f32_16x16x32_bf16 v[32:35], v[92:95], v[28:31], v[32:35]
	s_waitcnt lgkmcnt(0)
	s_nop 6
	v_fma_f32 v32, v90, v91, v32
	v_mul_f32_e32 v91, 0x3d372713, v32
	v_mul_f32_e32 v91, v32, v91
	v_fma_f32 v91, v32, v91, v32
	v_mul_f32_e32 v91, 0x3f4c422a, v91
	v_add_f32_e32 v91, v91, v91
	v_mul_f32_e32 v91, 0x3fb8aa3b, v91
	v_exp_f32_e32 v91, v91
	v_mul_f32_e32 v32, 0.5, v32
	v_add_f32_e32 v91, 1.0, v91
	v_div_scale_f32 v92, s[10:11], v91, v91, 2.0
	v_rcp_f32_e32 v93, v92
	s_nop 0
	v_fma_f32 v94, -v92, v93, 1.0
	v_fmac_f32_e32 v93, v94, v93
	v_div_scale_f32 v94, vcc, 2.0, v91, 2.0
	v_mul_f32_e32 v95, v94, v93
	v_fma_f32 v96, -v92, v95, v94
	v_fmac_f32_e32 v95, v96, v93
	v_fma_f32 v92, -v92, v95, v94
	v_div_fmas_f32 v92, v92, v93, v95
	v_div_fixup_f32 v91, v92, v91, 2.0
	v_sub_f32_e32 v91, 1.0, v91
	v_add_f32_e32 v91, 1.0, v91
	v_or3_b32 v92, s0, v81, v62
	v_mov_b32_e32 v93, v63
	v_mul_f32_e32 v32, v32, v91
	v_lshlrev_b64 v[92:93], 9, v[92:93]
	v_cvt_pk_bf16_f32 v32, v32, s0
	v_lshl_add_u64 v[92:93], v[66:67], 0, v[92:93]
	global_store_short v[92:93], v32, off
	ds_read_b32 v32, v87
	s_waitcnt lgkmcnt(0)
	v_fma_f32 v32, v90, v32, v33
	v_mul_f32_e32 v33, 0x3d372713, v32
	v_mul_f32_e32 v33, v32, v33
	v_fma_f32 v33, v32, v33, v32
	v_mul_f32_e32 v33, 0x3f4c422a, v33
	v_add_f32_e32 v33, v33, v33
	v_mul_f32_e32 v33, 0x3fb8aa3b, v33
	v_exp_f32_e32 v33, v33
	v_mul_f32_e32 v32, 0.5, v32
	v_add_f32_e32 v33, 1.0, v33
	v_div_scale_f32 v91, s[10:11], v33, v33, 2.0
	v_rcp_f32_e32 v92, v91
	s_nop 0
	v_fma_f32 v93, -v91, v92, 1.0
	v_fmac_f32_e32 v92, v93, v92
	v_div_scale_f32 v93, vcc, 2.0, v33, 2.0
	v_mul_f32_e32 v94, v93, v92
	v_fma_f32 v95, -v91, v94, v93
	v_fmac_f32_e32 v94, v95, v92
	v_fma_f32 v91, -v91, v94, v93
	v_div_fmas_f32 v91, v91, v92, v94
	v_div_fixup_f32 v33, v91, v33, 2.0
	v_sub_f32_e32 v33, 1.0, v33
	v_add_f32_e32 v33, 1.0, v33
	v_mul_f32_e32 v32, v32, v33
	v_cvt_pk_bf16_f32 v91, v32, s0
	v_or3_b32 v32, s0, v82, v62
	v_mov_b32_e32 v33, v63
	v_lshlrev_b64 v[32:33], 9, v[32:33]
	v_lshl_add_u64 v[32:33], v[66:67], 0, v[32:33]
	global_store_short v[32:33], v91, off
	ds_read_b32 v32, v88
	s_waitcnt lgkmcnt(0)
	v_fma_f32 v32, v90, v32, v34
	v_mul_f32_e32 v33, 0x3d372713, v32
	v_mul_f32_e32 v33, v32, v33
	v_fma_f32 v33, v32, v33, v32
	v_mul_f32_e32 v33, 0x3f4c422a, v33
	v_add_f32_e32 v33, v33, v33
	v_mul_f32_e32 v33, 0x3fb8aa3b, v33
	v_exp_f32_e32 v33, v33
	v_mul_f32_e32 v32, 0.5, v32
	v_add_f32_e32 v33, 1.0, v33
	v_div_scale_f32 v34, s[10:11], v33, v33, 2.0
	v_rcp_f32_e32 v91, v34
	s_nop 0
	v_fma_f32 v92, -v34, v91, 1.0
	v_fmac_f32_e32 v91, v92, v91
	v_div_scale_f32 v92, vcc, 2.0, v33, 2.0
	v_mul_f32_e32 v93, v92, v91
	v_fma_f32 v94, -v34, v93, v92
	v_fmac_f32_e32 v93, v94, v91
	v_fma_f32 v34, -v34, v93, v92
	v_div_fmas_f32 v34, v34, v91, v93
	v_div_fixup_f32 v33, v34, v33, 2.0
	v_sub_f32_e32 v33, 1.0, v33
	v_add_f32_e32 v33, 1.0, v33
	v_mul_f32_e32 v32, v32, v33
	v_cvt_pk_bf16_f32 v34, v32, s0
	v_or3_b32 v32, s0, v83, v62
	v_mov_b32_e32 v33, v63
	v_lshlrev_b64 v[32:33], 9, v[32:33]
	v_lshl_add_u64 v[32:33], v[66:67], 0, v[32:33]
	global_store_short v[32:33], v34, off
	ds_read_b32 v32, v89
	s_waitcnt lgkmcnt(0)
	v_fmac_f32_e32 v35, v90, v32
	v_mul_f32_e32 v32, 0x3d372713, v35
	v_mul_f32_e32 v32, v35, v32
	v_fma_f32 v32, v35, v32, v35
	v_mul_f32_e32 v32, 0x3f4c422a, v32
	v_add_f32_e32 v32, v32, v32
	v_mul_f32_e32 v32, 0x3fb8aa3b, v32
	v_exp_f32_e32 v32, v32
	s_nop 0
	v_add_f32_e32 v32, 1.0, v32
	v_div_scale_f32 v33, s[10:11], v32, v32, 2.0
	v_rcp_f32_e32 v34, v33
	s_nop 0
	v_fma_f32 v91, -v33, v34, 1.0
	v_fmac_f32_e32 v34, v91, v34
	v_div_scale_f32 v91, vcc, 2.0, v32, 2.0
	v_mul_f32_e32 v92, v91, v34
	v_fma_f32 v93, -v33, v92, v91
	v_fmac_f32_e32 v92, v93, v34
	v_fma_f32 v33, -v33, v92, v91
	v_div_fmas_f32 v33, v33, v34, v92
	v_div_fixup_f32 v32, v33, v32, 2.0
	v_sub_f32_e32 v32, 1.0, v32
	v_mul_f32_e32 v33, 0.5, v35
	v_add_f32_e32 v32, 1.0, v32
	v_mul_f32_e32 v32, v33, v32
	v_cvt_pk_bf16_f32 v34, v32, s0
	v_or3_b32 v32, s0, v84, v62
	v_mov_b32_e32 v33, v63
	v_lshlrev_b64 v[32:33], 9, v[32:33]
	v_lshl_add_u64 v[32:33], v[66:67], 0, v[32:33]
	global_store_short v[32:33], v34, off
	s_waitcnt lgkmcnt(0)
	s_cbranch_scc0 .LBB0_573
	v_readlane_b32 s0, v253, 16
	s_add_i32 s12, s12, s0
	s_cmpk_gt_i32 s12, 0x1ff
	v_readlane_b32 s1, v253, 17
	s_cbranch_scc0 .LBB0_568
	s_mov_b32 s64, s13
	s_mov_b32 s67, s26
	s_mov_b32 s66, s28
